# P10 act phase: fast path with all 8 strided elements' loads issued together (2 round trips instead of 24); original loop kept as remainder
# baseline (speedup 1.0000x reference)
; DI void phase10(const Params& p) {
;     ...
;   for (int i = blockIdx.x * 256 + threadIdx.x; i < T_ * 128; i += gridDim.x * 256) {
;     int ai = 0;
; #pragma unroll
;     for (int s = 0; s < 8; ++s) ai += PA[(size_t)s * T_ * 128 + i];
;     const int id = IDS[i];
;     const float a = (float)ai * USC[id] * HSC[i >> 7];
;     ACT[i] = 0.5f * a * (1.f + erff(a * 0.70710678118654752f)) * GATE[i] * VSC[id];
;   }
.LBB0_1187:
	s_waitcnt lgkmcnt(0)
	v_lshl_add_u32 v2, s12, 8, v0
	s_load_dword s13, s[0:1], 0xc0
	s_add_u32 s4, s82, 0x10638000
	s_addc_u32 s5, s83, 0
	s_add_u32 s6, s82, 0x16f18000
	s_addc_u32 s7, s83, 0
	s_add_u32 s8, s82, 0x18318000
	s_addc_u32 s9, s83, 0
	s_add_u32 s10, s82, 0x16638000
	s_addc_u32 s11, s83, 0
	s_add_u32 s14, s82, 0x16a38000
	s_addc_u32 s15, s83, 0
	s_add_u32 s16, s82, 0x16e38000
	s_addc_u32 s17, s83, 0
	s_add_u32 s18, s82, 0x16e48000
	s_addc_u32 s19, s83, 0
	s_mov_b32 s24, 0x378e98ab
	s_mov_b32 s25, 0x3b7cd369
	s_mov_b32 s26, 0xbcc618b2
	s_mov_b32 s27, 0x3dda74e4
	s_mov_b32 s28, 0x3f228afd
	s_mov_b32 s29, 0x3e03c728
	s_mov_b32 s30, 0xbfb8aa3b
	s_mov_b32 s31, 0x42ce8ed0
	s_mov_b32 s34, 0xc2b17218
	s_brev_b32 s35, -2
	v_mov_b32_e32 v1, 0x3ba10414
	v_mov_b32_e32 v8, 0xb9c68948
	v_mov_b32_e32 v9, 0x7f800000
	s_mov_b32 s21, 0x100000
	s_mov_b64 s[2:3], exec
	s_waitcnt lgkmcnt(0)
	s_lshl_b32 s13, s13, 8
	s_mul_i32 s20, s13, 7
.Lp10_fl:
	v_add_u32_e32 v3, s20, v2
	v_cmp_gt_i32_e32 vcc, s21, v3
	s_and_b64 exec, vcc, s[2:3]
	s_cbranch_execz .Lp10_fdone
	v_lshlrev_b32_e32 v10, 2, v2
	v_ashrrev_i32_e32 v26, 7, v2
	v_add_u32_e32 v4, s13, v2
	v_lshlrev_b32_e32 v11, 2, v4
	v_ashrrev_i32_e32 v27, 7, v4
	v_add_u32_e32 v4, s13, v4
	v_lshlrev_b32_e32 v12, 2, v4
	v_ashrrev_i32_e32 v28, 7, v4
	v_add_u32_e32 v4, s13, v4
	v_lshlrev_b32_e32 v13, 2, v4
	v_ashrrev_i32_e32 v29, 7, v4
	v_add_u32_e32 v4, s13, v4
	v_lshlrev_b32_e32 v14, 2, v4
	v_ashrrev_i32_e32 v30, 7, v4
	v_add_u32_e32 v4, s13, v4
	v_lshlrev_b32_e32 v15, 2, v4
	v_ashrrev_i32_e32 v31, 7, v4
	v_add_u32_e32 v4, s13, v4
	v_lshlrev_b32_e32 v16, 2, v4
	v_ashrrev_i32_e32 v32, 7, v4
	v_add_u32_e32 v4, s13, v4
	v_lshlrev_b32_e32 v17, 2, v4
	v_ashrrev_i32_e32 v33, 7, v4
	v_lshlrev_b32_e32 v26, 2, v26
	v_lshlrev_b32_e32 v27, 2, v27
	v_lshlrev_b32_e32 v28, 2, v28
	v_lshlrev_b32_e32 v29, 2, v29
	v_lshlrev_b32_e32 v30, 2, v30
	v_lshlrev_b32_e32 v31, 2, v31
	v_lshlrev_b32_e32 v32, 2, v32
	v_lshlrev_b32_e32 v33, 2, v33
	global_load_dword v18, v10, s[10:11]
	global_load_dword v19, v11, s[10:11]
	global_load_dword v20, v12, s[10:11]
	global_load_dword v21, v13, s[10:11]
	global_load_dword v22, v14, s[10:11]
	global_load_dword v23, v15, s[10:11]
	global_load_dword v24, v16, s[10:11]
	global_load_dword v25, v17, s[10:11]
	global_load_dword v66, v10, s[4:5]
	global_load_dword v67, v11, s[4:5]
	global_load_dword v68, v12, s[4:5]
	global_load_dword v69, v13, s[4:5]
	global_load_dword v70, v14, s[4:5]
	global_load_dword v71, v15, s[4:5]
	global_load_dword v72, v16, s[4:5]
	global_load_dword v73, v17, s[4:5]
	s_add_u32 s4, s4, 0x400000
	s_addc_u32 s5, s5, 0
	global_load_dword v74, v10, s[4:5]
	global_load_dword v75, v11, s[4:5]
	global_load_dword v76, v12, s[4:5]
	global_load_dword v77, v13, s[4:5]
	global_load_dword v78, v14, s[4:5]
	global_load_dword v79, v15, s[4:5]
	global_load_dword v80, v16, s[4:5]
	global_load_dword v81, v17, s[4:5]
	s_add_u32 s4, s4, 0x400000
	s_addc_u32 s5, s5, 0
	global_load_dword v82, v10, s[4:5]
	global_load_dword v83, v11, s[4:5]
	global_load_dword v84, v12, s[4:5]
	global_load_dword v85, v13, s[4:5]
	global_load_dword v86, v14, s[4:5]
	global_load_dword v87, v15, s[4:5]
	global_load_dword v88, v16, s[4:5]
	global_load_dword v89, v17, s[4:5]
	s_add_u32 s4, s4, 0x400000
	s_addc_u32 s5, s5, 0
	global_load_dword v90, v10, s[4:5]
	global_load_dword v91, v11, s[4:5]
	global_load_dword v92, v12, s[4:5]
	global_load_dword v93, v13, s[4:5]
	global_load_dword v94, v14, s[4:5]
	global_load_dword v95, v15, s[4:5]
	global_load_dword v96, v16, s[4:5]
	global_load_dword v97, v17, s[4:5]
	s_add_u32 s4, s4, 0x400000
	s_addc_u32 s5, s5, 0
	global_load_dword v34, v26, s[8:9]
	global_load_dword v35, v27, s[8:9]
	global_load_dword v36, v28, s[8:9]
	global_load_dword v37, v29, s[8:9]
	global_load_dword v38, v30, s[8:9]
	global_load_dword v39, v31, s[8:9]
	global_load_dword v40, v32, s[8:9]
	global_load_dword v41, v33, s[8:9]
	global_load_dword v42, v10, s[14:15]
	global_load_dword v43, v11, s[14:15]
	global_load_dword v44, v12, s[14:15]
	global_load_dword v45, v13, s[14:15]
	global_load_dword v46, v14, s[14:15]
	global_load_dword v47, v15, s[14:15]
	global_load_dword v48, v16, s[14:15]
	global_load_dword v49, v17, s[14:15]
	s_waitcnt vmcnt(55)
	v_lshlrev_b32_e32 v18, 2, v18
	global_load_dword v50, v18, s[16:17]
	global_load_dword v58, v18, s[18:19]
	s_waitcnt vmcnt(56)
	v_lshlrev_b32_e32 v19, 2, v19
	global_load_dword v51, v19, s[16:17]
	global_load_dword v59, v19, s[18:19]
	s_waitcnt vmcnt(57)
	v_lshlrev_b32_e32 v20, 2, v20
	global_load_dword v52, v20, s[16:17]
	global_load_dword v60, v20, s[18:19]
	s_waitcnt vmcnt(58)
	v_lshlrev_b32_e32 v21, 2, v21
	global_load_dword v53, v21, s[16:17]
	global_load_dword v61, v21, s[18:19]
	s_waitcnt vmcnt(59)
	v_lshlrev_b32_e32 v22, 2, v22
	global_load_dword v54, v22, s[16:17]
	global_load_dword v62, v22, s[18:19]
	s_waitcnt vmcnt(60)
	v_lshlrev_b32_e32 v23, 2, v23
	global_load_dword v55, v23, s[16:17]
	global_load_dword v63, v23, s[18:19]
	s_waitcnt vmcnt(61)
	v_lshlrev_b32_e32 v24, 2, v24
	global_load_dword v56, v24, s[16:17]
	global_load_dword v64, v24, s[18:19]
	s_waitcnt vmcnt(62)
	v_lshlrev_b32_e32 v25, 2, v25
	global_load_dword v57, v25, s[16:17]
	global_load_dword v65, v25, s[18:19]
	global_load_dword v98, v10, s[4:5]
	global_load_dword v99, v11, s[4:5]
	global_load_dword v100, v12, s[4:5]
	global_load_dword v101, v13, s[4:5]
	global_load_dword v102, v14, s[4:5]
	global_load_dword v103, v15, s[4:5]
	global_load_dword v104, v16, s[4:5]
	global_load_dword v105, v17, s[4:5]
	s_add_u32 s4, s4, 0x400000
	s_addc_u32 s5, s5, 0
	global_load_dword v106, v10, s[4:5]
	global_load_dword v107, v11, s[4:5]
	global_load_dword v108, v12, s[4:5]
	global_load_dword v109, v13, s[4:5]
	global_load_dword v110, v14, s[4:5]
	global_load_dword v111, v15, s[4:5]
	global_load_dword v112, v16, s[4:5]
	global_load_dword v113, v17, s[4:5]
	s_add_u32 s4, s4, 0x400000
	s_addc_u32 s5, s5, 0
	global_load_dword v114, v10, s[4:5]
	global_load_dword v115, v11, s[4:5]
	global_load_dword v116, v12, s[4:5]
	global_load_dword v117, v13, s[4:5]
	global_load_dword v118, v14, s[4:5]
	global_load_dword v119, v15, s[4:5]
	global_load_dword v120, v16, s[4:5]
	global_load_dword v121, v17, s[4:5]
	s_add_u32 s4, s4, 0x400000
	s_addc_u32 s5, s5, 0
	global_load_dword v122, v10, s[4:5]
	global_load_dword v123, v11, s[4:5]
	global_load_dword v124, v12, s[4:5]
	global_load_dword v125, v13, s[4:5]
	global_load_dword v126, v14, s[4:5]
	global_load_dword v127, v15, s[4:5]
	global_load_dword v128, v16, s[4:5]
	global_load_dword v129, v17, s[4:5]
	s_sub_u32 s4, s4, 0x1c00000
	s_subb_u32 s5, s5, 0
	s_waitcnt vmcnt(0)
	v_add_u32_e32 v3, v74, v66
	v_add3_u32 v3, v3, v82, v90
	v_add3_u32 v3, v3, v98, v106
	v_add3_u32 v3, v3, v114, v122
	v_cvt_f32_i32_e32 v3, v3
	v_mul_f32_e32 v3, v50, v3
	v_mul_f32_e32 v3, v3, v34
	v_mul_f32_e32 v130, 0x3f3504f3, v3
	v_cmp_nlt_f32_e64 s[22:23], |v130|, 1.0
	s_and_saveexec_b64 s[40:41], s[22:23]
	s_xor_b64 s[22:23], exec, s[40:41]
	s_cbranch_execz .Lp10_a0
; DI void phase10(const Params& p) {
;     ...
;     const float a = (float)ai * USC[id] * HSC[i >> 7];
;     ACT[i] = 0.5f * a * (1.f + erff(a * 0.70710678118654752f)) * GATE[i] * VSC[id];
	v_fma_f32 v131, |v130|, s24, v8
	v_fma_f32 v131, |v130|, v131, s25
	v_fma_f32 v131, |v130|, v131, s26
	v_fma_f32 v131, |v130|, v131, s27
	v_fma_f32 v131, |v130|, v131, s28
	v_fma_f32 v131, |v130|, v131, s29
	v_fma_f32 v131, |v130|, v131, |v130|
	v_mul_f32_e32 v132, 0xbfb8aa3b, v131
	v_fma_f32 v133, v131, s30, -v132
	v_rndne_f32_e32 v134, v132
	v_fmac_f32_e32 v133, 0xb2a5705f, v131
	v_sub_f32_e32 v132, v132, v134
	v_add_f32_e32 v132, v132, v133
	v_cvt_i32_f32_e32 v133, v134
	v_exp_f32_e32 v132, v132
	v_cmp_nlt_f32_e32 vcc, s31, v131
	v_ldexp_f32 v132, v132, v133
	s_nop 0
	v_cndmask_b32_e32 v132, 0, v132, vcc
	v_cmp_ngt_f32_e32 vcc, s34, v131
	s_nop 1
	v_cndmask_b32_e32 v131, v9, v132, vcc
	v_sub_f32_e32 v131, 1.0, v131
.Lp10_a0:
	s_andn2_saveexec_b64 s[22:23], s[22:23]
	s_cbranch_execz .Lp10_b0
	v_mul_f32_e32 v131, v130, v130
	v_fmamk_f32 v132, v131, 0xba1345e1, v1
	v_fmaak_f32 v132, v131, v132, 0xbcdac9b8
	v_fmaak_f32 v132, v131, v132, 0x3de703be
	v_fmaak_f32 v132, v131, v132, 0xbec09330
	v_fmaak_f32 v131, v131, v132, 0x3e0375d0
	v_fma_f32 v131, |v130|, v131, |v130|
.Lp10_b0:
	s_or_b64 exec, exec, s[22:23]
	v_bfi_b32 v6, s35, v131, v130
	v_mul_f32_e32 v3, 0.5, v3
	v_add_f32_e32 v6, 1.0, v6
	v_mul_f32_e32 v3, v3, v6
	v_mul_f32_e32 v3, v42, v3
	v_mul_f32_e32 v136, v58, v3
	global_store_dword v10, v136, s[6:7]
	v_add_u32_e32 v3, v75, v67
	v_add3_u32 v3, v3, v83, v91
	v_add3_u32 v3, v3, v99, v107
	v_add3_u32 v3, v3, v115, v123
	v_cvt_f32_i32_e32 v3, v3
	v_mul_f32_e32 v3, v51, v3
	v_mul_f32_e32 v3, v3, v35
	v_mul_f32_e32 v130, 0x3f3504f3, v3
	v_cmp_nlt_f32_e64 s[22:23], |v130|, 1.0
	s_and_saveexec_b64 s[40:41], s[22:23]
	s_xor_b64 s[22:23], exec, s[40:41]
	s_cbranch_execz .Lp10_a1
	v_fma_f32 v131, |v130|, s24, v8
	v_fma_f32 v131, |v130|, v131, s25
	v_fma_f32 v131, |v130|, v131, s26
	v_fma_f32 v131, |v130|, v131, s27
	v_fma_f32 v131, |v130|, v131, s28
	v_fma_f32 v131, |v130|, v131, s29
	v_fma_f32 v131, |v130|, v131, |v130|
	v_mul_f32_e32 v132, 0xbfb8aa3b, v131
	v_fma_f32 v133, v131, s30, -v132
	v_rndne_f32_e32 v134, v132
	v_fmac_f32_e32 v133, 0xb2a5705f, v131
	v_sub_f32_e32 v132, v132, v134
	v_add_f32_e32 v132, v132, v133
	v_cvt_i32_f32_e32 v133, v134
	v_exp_f32_e32 v132, v132
	v_cmp_nlt_f32_e32 vcc, s31, v131
	v_ldexp_f32 v132, v132, v133
	s_nop 0
	v_cndmask_b32_e32 v132, 0, v132, vcc
	v_cmp_ngt_f32_e32 vcc, s34, v131
	s_nop 1
	v_cndmask_b32_e32 v131, v9, v132, vcc
	v_sub_f32_e32 v131, 1.0, v131

; DI void phase10(const Params& p) {
;     ...
;     const float a = (float)ai * USC[id] * HSC[i >> 7];
;     ACT[i] = 0.5f * a * (1.f + erff(a * 0.70710678118654752f)) * GATE[i] * VSC[id];
.Lp10_b1:
	s_or_b64 exec, exec, s[22:23]
	v_bfi_b32 v6, s35, v131, v130
	v_mul_f32_e32 v3, 0.5, v3
	v_add_f32_e32 v6, 1.0, v6
	v_mul_f32_e32 v3, v3, v6
	v_mul_f32_e32 v3, v43, v3
	v_mul_f32_e32 v137, v59, v3
	global_store_dword v11, v137, s[6:7]
	v_add_u32_e32 v3, v76, v68
	v_add3_u32 v3, v3, v84, v92
	v_add3_u32 v3, v3, v100, v108
	v_add3_u32 v3, v3, v116, v124
	v_cvt_f32_i32_e32 v3, v3
	v_mul_f32_e32 v3, v52, v3
	v_mul_f32_e32 v3, v3, v36
	v_mul_f32_e32 v130, 0x3f3504f3, v3
	v_cmp_nlt_f32_e64 s[22:23], |v130|, 1.0
	s_and_saveexec_b64 s[40:41], s[22:23]
	s_xor_b64 s[22:23], exec, s[40:41]
	s_cbranch_execz .Lp10_a2
	v_fma_f32 v131, |v130|, s24, v8
	v_fma_f32 v131, |v130|, v131, s25
	v_fma_f32 v131, |v130|, v131, s26
	v_fma_f32 v131, |v130|, v131, s27
	v_fma_f32 v131, |v130|, v131, s28
	v_fma_f32 v131, |v130|, v131, s29
	v_fma_f32 v131, |v130|, v131, |v130|
	v_mul_f32_e32 v132, 0xbfb8aa3b, v131
	v_fma_f32 v133, v131, s30, -v132
	v_rndne_f32_e32 v134, v132
	v_fmac_f32_e32 v133, 0xb2a5705f, v131
	v_sub_f32_e32 v132, v132, v134
	v_add_f32_e32 v132, v132, v133
	v_cvt_i32_f32_e32 v133, v134
	v_exp_f32_e32 v132, v132
	v_cmp_nlt_f32_e32 vcc, s31, v131
	v_ldexp_f32 v132, v132, v133
	s_nop 0
	v_cndmask_b32_e32 v132, 0, v132, vcc
	v_cmp_ngt_f32_e32 vcc, s34, v131
	s_nop 1
	v_cndmask_b32_e32 v131, v9, v132, vcc
	v_sub_f32_e32 v131, 1.0, v131

; DI void phase10(const Params& p) {
;     ...
;     const float a = (float)ai * USC[id] * HSC[i >> 7];
;     ACT[i] = 0.5f * a * (1.f + erff(a * 0.70710678118654752f)) * GATE[i] * VSC[id];
.Lp10_b2:
	s_or_b64 exec, exec, s[22:23]
	v_bfi_b32 v6, s35, v131, v130
	v_mul_f32_e32 v3, 0.5, v3
	v_add_f32_e32 v6, 1.0, v6
	v_mul_f32_e32 v3, v3, v6
	v_mul_f32_e32 v3, v44, v3
	v_mul_f32_e32 v138, v60, v3
	global_store_dword v12, v138, s[6:7]
	v_add_u32_e32 v3, v77, v69
	v_add3_u32 v3, v3, v85, v93
	v_add3_u32 v3, v3, v101, v109
	v_add3_u32 v3, v3, v117, v125
	v_cvt_f32_i32_e32 v3, v3
	v_mul_f32_e32 v3, v53, v3
	v_mul_f32_e32 v3, v3, v37
	v_mul_f32_e32 v130, 0x3f3504f3, v3
	v_cmp_nlt_f32_e64 s[22:23], |v130|, 1.0
	s_and_saveexec_b64 s[40:41], s[22:23]
	s_xor_b64 s[22:23], exec, s[40:41]
	s_cbranch_execz .Lp10_a3
	v_fma_f32 v131, |v130|, s24, v8
	v_fma_f32 v131, |v130|, v131, s25
	v_fma_f32 v131, |v130|, v131, s26
	v_fma_f32 v131, |v130|, v131, s27
	v_fma_f32 v131, |v130|, v131, s28
	v_fma_f32 v131, |v130|, v131, s29
	v_fma_f32 v131, |v130|, v131, |v130|
	v_mul_f32_e32 v132, 0xbfb8aa3b, v131
	v_fma_f32 v133, v131, s30, -v132
	v_rndne_f32_e32 v134, v132
	v_fmac_f32_e32 v133, 0xb2a5705f, v131
	v_sub_f32_e32 v132, v132, v134
	v_add_f32_e32 v132, v132, v133
	v_cvt_i32_f32_e32 v133, v134
	v_exp_f32_e32 v132, v132
	v_cmp_nlt_f32_e32 vcc, s31, v131
	v_ldexp_f32 v132, v132, v133
	s_nop 0
	v_cndmask_b32_e32 v132, 0, v132, vcc
	v_cmp_ngt_f32_e32 vcc, s34, v131
	s_nop 1
	v_cndmask_b32_e32 v131, v9, v132, vcc
	v_sub_f32_e32 v131, 1.0, v131

; DI void phase10(const Params& p) {
;     ...
;     const float a = (float)ai * USC[id] * HSC[i >> 7];
;     ACT[i] = 0.5f * a * (1.f + erff(a * 0.70710678118654752f)) * GATE[i] * VSC[id];
.Lp10_b3:
	s_or_b64 exec, exec, s[22:23]
	v_bfi_b32 v6, s35, v131, v130
	v_mul_f32_e32 v3, 0.5, v3
	v_add_f32_e32 v6, 1.0, v6
	v_mul_f32_e32 v3, v3, v6
	v_mul_f32_e32 v3, v45, v3
	v_mul_f32_e32 v139, v61, v3
	global_store_dword v13, v139, s[6:7]
	v_add_u32_e32 v3, v78, v70
	v_add3_u32 v3, v3, v86, v94
	v_add3_u32 v3, v3, v102, v110
	v_add3_u32 v3, v3, v118, v126
	v_cvt_f32_i32_e32 v3, v3
	v_mul_f32_e32 v3, v54, v3
	v_mul_f32_e32 v3, v3, v38
	v_mul_f32_e32 v130, 0x3f3504f3, v3
	v_cmp_nlt_f32_e64 s[22:23], |v130|, 1.0
	s_and_saveexec_b64 s[40:41], s[22:23]
	s_xor_b64 s[22:23], exec, s[40:41]
	s_cbranch_execz .Lp10_a4
	v_fma_f32 v131, |v130|, s24, v8
	v_fma_f32 v131, |v130|, v131, s25
	v_fma_f32 v131, |v130|, v131, s26
	v_fma_f32 v131, |v130|, v131, s27
	v_fma_f32 v131, |v130|, v131, s28
	v_fma_f32 v131, |v130|, v131, s29
	v_fma_f32 v131, |v130|, v131, |v130|
	v_mul_f32_e32 v132, 0xbfb8aa3b, v131
	v_fma_f32 v133, v131, s30, -v132
	v_rndne_f32_e32 v134, v132
	v_fmac_f32_e32 v133, 0xb2a5705f, v131
	v_sub_f32_e32 v132, v132, v134
	v_add_f32_e32 v132, v132, v133
	v_cvt_i32_f32_e32 v133, v134
	v_exp_f32_e32 v132, v132
	v_cmp_nlt_f32_e32 vcc, s31, v131
	v_ldexp_f32 v132, v132, v133
	s_nop 0
	v_cndmask_b32_e32 v132, 0, v132, vcc
	v_cmp_ngt_f32_e32 vcc, s34, v131
	s_nop 1
	v_cndmask_b32_e32 v131, v9, v132, vcc
	v_sub_f32_e32 v131, 1.0, v131

; DI void phase10(const Params& p) {
;     ...
;     const float a = (float)ai * USC[id] * HSC[i >> 7];
;     ACT[i] = 0.5f * a * (1.f + erff(a * 0.70710678118654752f)) * GATE[i] * VSC[id];
.Lp10_b4:
	s_or_b64 exec, exec, s[22:23]
	v_bfi_b32 v6, s35, v131, v130
	v_mul_f32_e32 v3, 0.5, v3
	v_add_f32_e32 v6, 1.0, v6
	v_mul_f32_e32 v3, v3, v6
	v_mul_f32_e32 v3, v46, v3
	v_mul_f32_e32 v140, v62, v3
	global_store_dword v14, v140, s[6:7]
	v_add_u32_e32 v3, v79, v71
	v_add3_u32 v3, v3, v87, v95
	v_add3_u32 v3, v3, v103, v111
	v_add3_u32 v3, v3, v119, v127
	v_cvt_f32_i32_e32 v3, v3
	v_mul_f32_e32 v3, v55, v3
	v_mul_f32_e32 v3, v3, v39
	v_mul_f32_e32 v130, 0x3f3504f3, v3
	v_cmp_nlt_f32_e64 s[22:23], |v130|, 1.0
	s_and_saveexec_b64 s[40:41], s[22:23]
	s_xor_b64 s[22:23], exec, s[40:41]
	s_cbranch_execz .Lp10_a5
	v_fma_f32 v131, |v130|, s24, v8
	v_fma_f32 v131, |v130|, v131, s25
	v_fma_f32 v131, |v130|, v131, s26
	v_fma_f32 v131, |v130|, v131, s27
	v_fma_f32 v131, |v130|, v131, s28
	v_fma_f32 v131, |v130|, v131, s29
	v_fma_f32 v131, |v130|, v131, |v130|
	v_mul_f32_e32 v132, 0xbfb8aa3b, v131
	v_fma_f32 v133, v131, s30, -v132
	v_rndne_f32_e32 v134, v132
	v_fmac_f32_e32 v133, 0xb2a5705f, v131
	v_sub_f32_e32 v132, v132, v134
	v_add_f32_e32 v132, v132, v133
	v_cvt_i32_f32_e32 v133, v134
	v_exp_f32_e32 v132, v132
	v_cmp_nlt_f32_e32 vcc, s31, v131
	v_ldexp_f32 v132, v132, v133
	s_nop 0
	v_cndmask_b32_e32 v132, 0, v132, vcc
	v_cmp_ngt_f32_e32 vcc, s34, v131
	s_nop 1
	v_cndmask_b32_e32 v131, v9, v132, vcc
	v_sub_f32_e32 v131, 1.0, v131

; DI void phase10(const Params& p) {
;     ...
;     const float a = (float)ai * USC[id] * HSC[i >> 7];
;     ACT[i] = 0.5f * a * (1.f + erff(a * 0.70710678118654752f)) * GATE[i] * VSC[id];
.Lp10_b5:
	s_or_b64 exec, exec, s[22:23]
	v_bfi_b32 v6, s35, v131, v130
	v_mul_f32_e32 v3, 0.5, v3
	v_add_f32_e32 v6, 1.0, v6
	v_mul_f32_e32 v3, v3, v6
	v_mul_f32_e32 v3, v47, v3
	v_mul_f32_e32 v141, v63, v3
	global_store_dword v15, v141, s[6:7]
	v_add_u32_e32 v3, v80, v72
	v_add3_u32 v3, v3, v88, v96
	v_add3_u32 v3, v3, v104, v112
	v_add3_u32 v3, v3, v120, v128
	v_cvt_f32_i32_e32 v3, v3
	v_mul_f32_e32 v3, v56, v3
	v_mul_f32_e32 v3, v3, v40
	v_mul_f32_e32 v130, 0x3f3504f3, v3
	v_cmp_nlt_f32_e64 s[22:23], |v130|, 1.0
	s_and_saveexec_b64 s[40:41], s[22:23]
	s_xor_b64 s[22:23], exec, s[40:41]
	s_cbranch_execz .Lp10_a6
	v_fma_f32 v131, |v130|, s24, v8
	v_fma_f32 v131, |v130|, v131, s25
	v_fma_f32 v131, |v130|, v131, s26
	v_fma_f32 v131, |v130|, v131, s27
	v_fma_f32 v131, |v130|, v131, s28
	v_fma_f32 v131, |v130|, v131, s29
	v_fma_f32 v131, |v130|, v131, |v130|
	v_mul_f32_e32 v132, 0xbfb8aa3b, v131
	v_fma_f32 v133, v131, s30, -v132
	v_rndne_f32_e32 v134, v132
	v_fmac_f32_e32 v133, 0xb2a5705f, v131
	v_sub_f32_e32 v132, v132, v134
	v_add_f32_e32 v132, v132, v133
	v_cvt_i32_f32_e32 v133, v134
	v_exp_f32_e32 v132, v132
	v_cmp_nlt_f32_e32 vcc, s31, v131
	v_ldexp_f32 v132, v132, v133
	s_nop 0
	v_cndmask_b32_e32 v132, 0, v132, vcc
	v_cmp_ngt_f32_e32 vcc, s34, v131
	s_nop 1
	v_cndmask_b32_e32 v131, v9, v132, vcc
	v_sub_f32_e32 v131, 1.0, v131

; DI void phase10(const Params& p) {
;     ...
;     const float a = (float)ai * USC[id] * HSC[i >> 7];
;     ACT[i] = 0.5f * a * (1.f + erff(a * 0.70710678118654752f)) * GATE[i] * VSC[id];
.Lp10_b6:
	s_or_b64 exec, exec, s[22:23]
	v_bfi_b32 v6, s35, v131, v130
	v_mul_f32_e32 v3, 0.5, v3
	v_add_f32_e32 v6, 1.0, v6
	v_mul_f32_e32 v3, v3, v6
	v_mul_f32_e32 v3, v48, v3
	v_mul_f32_e32 v142, v64, v3
	global_store_dword v16, v142, s[6:7]
	v_add_u32_e32 v3, v81, v73
	v_add3_u32 v3, v3, v89, v97
	v_add3_u32 v3, v3, v105, v113
	v_add3_u32 v3, v3, v121, v129
	v_cvt_f32_i32_e32 v3, v3
	v_mul_f32_e32 v3, v57, v3
	v_mul_f32_e32 v3, v3, v41
	v_mul_f32_e32 v130, 0x3f3504f3, v3
	v_cmp_nlt_f32_e64 s[22:23], |v130|, 1.0
	s_and_saveexec_b64 s[40:41], s[22:23]
	s_xor_b64 s[22:23], exec, s[40:41]
	s_cbranch_execz .Lp10_a7
	v_fma_f32 v131, |v130|, s24, v8
	v_fma_f32 v131, |v130|, v131, s25
	v_fma_f32 v131, |v130|, v131, s26
	v_fma_f32 v131, |v130|, v131, s27
	v_fma_f32 v131, |v130|, v131, s28
	v_fma_f32 v131, |v130|, v131, s29
	v_fma_f32 v131, |v130|, v131, |v130|
	v_mul_f32_e32 v132, 0xbfb8aa3b, v131
	v_fma_f32 v133, v131, s30, -v132
	v_rndne_f32_e32 v134, v132
	v_fmac_f32_e32 v133, 0xb2a5705f, v131
	v_sub_f32_e32 v132, v132, v134
	v_add_f32_e32 v132, v132, v133
	v_cvt_i32_f32_e32 v133, v134
	v_exp_f32_e32 v132, v132
	v_cmp_nlt_f32_e32 vcc, s31, v131
	v_ldexp_f32 v132, v132, v133
	s_nop 0
	v_cndmask_b32_e32 v132, 0, v132, vcc
	v_cmp_ngt_f32_e32 vcc, s34, v131
	s_nop 1
	v_cndmask_b32_e32 v131, v9, v132, vcc
	v_sub_f32_e32 v131, 1.0, v131

; DI void phase10(const Params& p) {
;     ...
;   for (int i = blockIdx.x * 256 + threadIdx.x; i < T_ * 128; i += gridDim.x * 256) {
;     int ai = 0;
; #pragma unroll
;     for (int s = 0; s < 8; ++s) ai += PA[(size_t)s * T_ * 128 + i];
;     const int id = IDS[i];
;     const float a = (float)ai * USC[id] * HSC[i >> 7];
;     ACT[i] = 0.5f * a * (1.f + erff(a * 0.70710678118654752f)) * GATE[i] * VSC[id];
;   }
.Lp10_b7:
	s_or_b64 exec, exec, s[22:23]
	v_bfi_b32 v6, s35, v131, v130
	v_mul_f32_e32 v3, 0.5, v3
	v_add_f32_e32 v6, 1.0, v6
	v_mul_f32_e32 v3, v3, v6
	v_mul_f32_e32 v3, v49, v3
	v_mul_f32_e32 v143, v65, v3
	global_store_dword v17, v143, s[6:7]
	v_lshl_add_u32 v2, s13, 3, v2
	s_branch .Lp10_fl
.Lp10_fdone:
	s_mov_b64 exec, s[2:3]
	s_mov_b32 s2, 0x100000
	v_cmp_gt_i32_e32 vcc, s2, v2
	s_and_saveexec_b64 s[2:3], vcc
	s_cbranch_execz .LBB0_1194
	s_add_u32 s4, s82, 0x10638000
	s_addc_u32 s5, s83, 0
	s_add_u32 s6, s82, 0x16f18000
	s_addc_u32 s7, s83, 0
	s_add_u32 s8, s82, 0x18318000
	s_addc_u32 s9, s83, 0
	s_add_u32 s10, s82, 0x16638000
	s_addc_u32 s11, s83, 0
	s_add_u32 s14, s82, 0x16a38000
	s_load_dword s13, s[0:1], 0xc0
	s_addc_u32 s15, s83, 0
	s_add_u32 s16, s82, 0x16e38000
	s_addc_u32 s17, s83, 0
	s_add_u32 s18, s82, 0x16e48000
	s_addc_u32 s19, s83, 0
	s_waitcnt lgkmcnt(0)
	s_lshl_b32 s13, s13, 8
	s_mov_b64 s[20:21], 0
	s_mov_b32 s24, 0x378e98ab
	s_mov_b32 s25, 0x3b7cd369
	s_mov_b32 s26, 0xbcc618b2
	s_mov_b32 s27, 0x3dda74e4
	s_mov_b32 s28, 0x3f228afd
	s_mov_b32 s29, 0x3e03c728
	s_mov_b32 s30, 0xbfb8aa3b
	s_mov_b32 s31, 0x42ce8ed0
	s_mov_b32 s34, 0xc2b17218
	v_mov_b32_e32 v1, 0x3ba10414
	s_brev_b32 s35, -2
	s_mov_b32 s36, 0xfffff
	v_mov_b32_e32 v8, 0xb9c68948
	v_mov_b32_e32 v9, 0x7f800000
	s_branch .LBB0_1190
